# grid-barrier census: sixteen per-XCC counter reads issued together instead of one dependent round trip each
# speedup vs baseline: 1.0041x; 1.0021x over previous
.LBB0_1032:
	global_load_dword v10, v1, s[14:15] sc1
	global_load_dword v11, v1, s[14:15] offset:256 sc1
	global_load_dword v12, v1, s[14:15] offset:512 sc1
	global_load_dword v13, v1, s[14:15] offset:768 sc1
	global_load_dword v14, v1, s[14:15] offset:1024 sc1
	global_load_dword v15, v1, s[14:15] offset:1280 sc1
	global_load_dword v16, v1, s[14:15] offset:1536 sc1
	global_load_dword v17, v1, s[14:15] offset:1792 sc1
	global_load_dword v18, v1, s[14:15] offset:2048 sc1
	global_load_dword v19, v1, s[14:15] offset:2304 sc1
	global_load_dword v20, v1, s[14:15] offset:2560 sc1
	global_load_dword v21, v1, s[14:15] offset:2816 sc1
	global_load_dword v22, v1, s[14:15] offset:3072 sc1
	global_load_dword v23, v1, s[14:15] offset:3328 sc1
	global_load_dword v24, v1, s[14:15] offset:3584 sc1
	global_load_dword v25, v1, s[14:15] offset:3840 sc1
	s_waitcnt vmcnt(0)
	v_cmp_ne_u32_e32 vcc, 0, v10
	s_cmp_lg_u64 vcc, 0
	s_addc_u32 s5, s5, 0
	v_add_u32_e32 v3, v10, v3
	v_cmp_ne_u32_e32 vcc, 0, v11
	s_cmp_lg_u64 vcc, 0
	s_addc_u32 s5, s5, 0
	v_add_u32_e32 v3, v11, v3
	v_cmp_ne_u32_e32 vcc, 0, v12
	s_cmp_lg_u64 vcc, 0
	s_addc_u32 s5, s5, 0
	v_add_u32_e32 v3, v12, v3
	v_cmp_ne_u32_e32 vcc, 0, v13
	s_cmp_lg_u64 vcc, 0
	s_addc_u32 s5, s5, 0
	v_add_u32_e32 v3, v13, v3
	v_cmp_ne_u32_e32 vcc, 0, v14
	s_cmp_lg_u64 vcc, 0
	s_addc_u32 s5, s5, 0
	v_add_u32_e32 v3, v14, v3
	v_cmp_ne_u32_e32 vcc, 0, v15
	s_cmp_lg_u64 vcc, 0
	s_addc_u32 s5, s5, 0
	v_add_u32_e32 v3, v15, v3
	v_cmp_ne_u32_e32 vcc, 0, v16
	s_cmp_lg_u64 vcc, 0
	s_addc_u32 s5, s5, 0
	v_add_u32_e32 v3, v16, v3
	v_cmp_ne_u32_e32 vcc, 0, v17
	s_cmp_lg_u64 vcc, 0
	s_addc_u32 s5, s5, 0
	v_add_u32_e32 v3, v17, v3
	v_cmp_ne_u32_e32 vcc, 0, v18
	s_cmp_lg_u64 vcc, 0
	s_addc_u32 s5, s5, 0
	v_add_u32_e32 v3, v18, v3
	v_cmp_ne_u32_e32 vcc, 0, v19
	s_cmp_lg_u64 vcc, 0
	s_addc_u32 s5, s5, 0
	v_add_u32_e32 v3, v19, v3
	v_cmp_ne_u32_e32 vcc, 0, v20
	s_cmp_lg_u64 vcc, 0
	s_addc_u32 s5, s5, 0
	v_add_u32_e32 v3, v20, v3
	v_cmp_ne_u32_e32 vcc, 0, v21
	s_cmp_lg_u64 vcc, 0
	s_addc_u32 s5, s5, 0
	v_add_u32_e32 v3, v21, v3
	v_cmp_ne_u32_e32 vcc, 0, v22
	s_cmp_lg_u64 vcc, 0
	s_addc_u32 s5, s5, 0
	v_add_u32_e32 v3, v22, v3
	v_cmp_ne_u32_e32 vcc, 0, v23
	s_cmp_lg_u64 vcc, 0
	s_addc_u32 s5, s5, 0
	v_add_u32_e32 v3, v23, v3
	v_cmp_ne_u32_e32 vcc, 0, v24
	s_cmp_lg_u64 vcc, 0
	s_addc_u32 s5, s5, 0
	v_add_u32_e32 v3, v24, v3
	v_cmp_ne_u32_e32 vcc, 0, v25
	s_cmp_lg_u64 vcc, 0
	s_addc_u32 s5, s5, 0
	v_add_u32_e32 v3, v25, v3
	global_load_dword v0, v1, s[8:9] sc1
	v_cmp_ne_u32_e32 vcc, s79, v3
	s_mov_b64 s[10:11], -1
	s_mov_b64 s[12:13], -1
	s_cbranch_vccz .LBB0_1030
	s_add_i32 s17, s17, 1
	s_and_b32 s12, s17, 0xff
	s_cmp_eq_u32 s12, 0
	s_cselect_b64 s[12:13], -1, 0
	s_and_b64 vcc, exec, s[12:13]
	s_sleep 1
	s_cbranch_vccz .LBB0_1030
	global_load_dword v3, v1, s[6:7] sc1
	s_waitcnt vmcnt(0)
	v_cmp_eq_u32_e32 vcc, 0, v3
	s_cbranch_vccz .LBB0_1030
	s_cmp_gt_u32 s17, 0x40000
	s_mov_b64 s[10:11], 0
	s_cselect_b64 s[12:13], -1, 0
	s_branch .LBB0_1030
